# LayerNorm loops (ln1, final) with all per-token loads hoisted to one wait, stacked on v42
# speedup vs baseline: 1.0059x; 1.0059x over previous
.LBB0_896:
	v_add_u32_e32 v2, 0xfffff000, v12
	v_lshrrev_b32_e32 v2, 10, v2
	v_ashrrev_i32_e32 v13, 31, v12
	v_add_u32_e32 v2, 1, v2
	v_cmp_lt_i32_e32 vcc, s61, v12
	v_lshlrev_b64 v[0:1], 12, v[12:13]
	v_lshl_add_u64 v[56:57], v[18:19], 0, v[0:1]
	v_cndmask_b32_e32 v4, 0, v2, vcc
	v_mov_b64_e32 v[2:3], s[36:37]
	v_mad_u64_u32 v[2:3], s[12:13], v4, s33, v[2:3]
	v_lshl_add_u64 v[34:35], v[2:3], 0, s[30:31]
	v_lshl_add_u64 v[32:33], v[2:3], 0, s[82:83]
	v_lshl_add_u64 v[38:39], v[20:21], 0, v[0:1]
	global_load_dwordx4 v[8:11], v[56:57], off
	global_load_dwordx4 v[0:3], v[14:15], off
	global_load_dwordx4 v[4:7], v[16:17], off
	global_load_dwordx4 v[52:55], v[56:57], off offset:1024
	global_load_dwordx4 v[68:71], v[56:57], off offset:2048
	global_load_dwordx4 v[72:75], v[56:57], off offset:3072
	v_lshlrev_b64 v[36:37], 11, v[12:13]
	v_mov_b32_e32 v25, v96
	v_lshl_add_u64 v[50:51], v[34:35], 0, v[24:25]
	v_lshl_add_u64 v[48:49], v[32:33], 0, v[24:25]
	v_lshl_add_u64 v[36:37], v[22:23], 0, v[36:37]
	v_mov_b32_e32 v27, v96
	v_lshl_add_u64 v[46:47], v[34:35], 0, v[26:27]
	v_lshl_add_u64 v[44:45], v[32:33], 0, v[26:27]
	v_mov_b32_e32 v29, v96
	v_mov_b32_e32 v31, v96
	v_add_u32_e32 v12, s47, v12
	global_load_dwordx4 v[100:103], v[50:51], off
	global_load_dwordx4 v[104:107], v[48:49], off
	global_load_dwordx4 v[108:111], v[14:15], off offset:1024
	global_load_dwordx4 v[112:115], v[16:17], off offset:1024
	global_load_dwordx4 v[116:119], v[46:47], off
	global_load_dwordx4 v[120:123], v[44:45], off
	global_load_dwordx4 v[124:127], v[14:15], off offset:2048
	global_load_dwordx4 v[128:131], v[16:17], off offset:2048
	v_lshl_add_u64 v[164:165], v[34:35], 0, v[28:29]
	global_load_dwordx4 v[132:135], v[164:165], off
	v_lshl_add_u64 v[166:167], v[32:33], 0, v[28:29]
	global_load_dwordx4 v[136:139], v[166:167], off
	global_load_dwordx4 v[140:143], v[14:15], off offset:3072
	global_load_dwordx4 v[144:147], v[16:17], off offset:3072
	v_lshl_add_u64 v[168:169], v[34:35], 0, v[30:31]
	global_load_dwordx4 v[148:151], v[168:169], off
	v_lshl_add_u64 v[170:171], v[32:33], 0, v[30:31]
	global_load_dwordx4 v[152:155], v[170:171], off
	s_waitcnt vmcnt(0)
	v_mov_b32_e32 v40, v8
	v_mov_b32_e32 v42, v9
	v_mov_b32_e32 v41, v52
	v_mov_b32_e32 v43, v53
	v_pk_add_f32 v[40:41], v[40:41], v[42:43]
	v_mov_b32_e32 v42, v10
	v_mov_b32_e32 v43, v54
	v_pk_add_f32 v[40:41], v[40:41], v[42:43]
	v_mov_b32_e32 v42, v11
	v_mov_b32_e32 v43, v55
	v_mov_b32_e32 v56, v68
	v_mov_b32_e32 v57, v72
	v_mov_b32_e32 v58, v69
	v_mov_b32_e32 v59, v73
	v_pk_add_f32 v[40:41], v[40:41], v[42:43]
	v_pk_add_f32 v[56:57], v[56:57], v[58:59]
	v_mov_b32_e32 v58, v70
	v_mov_b32_e32 v59, v74
	v_add_f32_e32 v13, 0, v40
	v_pk_add_f32 v[56:57], v[56:57], v[58:59]
	v_mov_b32_e32 v58, v71
	v_mov_b32_e32 v59, v75
	v_add_f32_e32 v13, v13, v41
	v_pk_add_f32 v[56:57], v[56:57], v[58:59]
	v_lshl_add_u64 v[42:43], v[34:35], 0, v[28:29]
	v_add_f32_e32 v13, v13, v56
	v_add_f32_e32 v13, v13, v57
	ds_bpermute_b32 v25, v61, v13
	v_lshl_add_u64 v[40:41], v[32:33], 0, v[28:29]
	s_waitcnt lgkmcnt(0)
	v_add_f32_e32 v13, v13, v25
	ds_bpermute_b32 v25, v62, v13
	s_waitcnt lgkmcnt(0)
	v_add_f32_e32 v13, v13, v25
	ds_bpermute_b32 v25, v63, v13
	s_waitcnt lgkmcnt(0)
	v_add_f32_e32 v13, v13, v25
	ds_bpermute_b32 v25, v64, v13
	s_waitcnt lgkmcnt(0)
	v_add_f32_e32 v13, v13, v25
	ds_bpermute_b32 v25, v65, v13
	s_waitcnt lgkmcnt(0)
	v_add_f32_e32 v13, v13, v25
	ds_bpermute_b32 v25, v66, v13
	s_waitcnt lgkmcnt(0)
	v_add_f32_e32 v13, v13, v25
	v_mul_f32_e32 v60, 0x3a800000, v13
	v_pk_add_f32 v[76:77], v[8:9], v[60:61] op_sel_hi:[1,0] neg_lo:[0,1] neg_hi:[0,1]
	v_pk_add_f32 v[58:59], v[52:53], v[60:61] op_sel_hi:[1,0] neg_lo:[0,1] neg_hi:[0,1]
	v_pk_add_f32 v[78:79], v[10:11], v[60:61] op_sel_hi:[1,0] neg_lo:[0,1] neg_hi:[0,1]
	v_mov_b32_e32 v10, v77
	v_mov_b32_e32 v11, v59
	v_pk_add_f32 v[56:57], v[54:55], v[60:61] op_sel_hi:[1,0] neg_lo:[0,1] neg_hi:[0,1]
	v_mov_b32_e32 v8, v76
	v_mov_b32_e32 v9, v58
	v_pk_mul_f32 v[10:11], v[10:11], v[10:11]
	v_pk_add_f32 v[54:55], v[68:69], v[60:61] op_sel_hi:[1,0] neg_lo:[0,1] neg_hi:[0,1]
	v_pk_fma_f32 v[8:9], v[8:9], v[8:9], v[10:11]
	v_mov_b32_e32 v10, v78
	v_mov_b32_e32 v11, v56
	v_pk_fma_f32 v[8:9], v[10:11], v[10:11], v[8:9]
	v_mov_b32_e32 v10, v79
	v_mov_b32_e32 v11, v57
	v_pk_fma_f32 v[80:81], v[10:11], v[10:11], v[8:9]
	v_pk_add_f32 v[10:11], v[72:73], v[60:61] op_sel_hi:[1,0] neg_lo:[0,1] neg_hi:[0,1]
	v_pk_add_f32 v[52:53], v[70:71], v[60:61] op_sel_hi:[1,0] neg_lo:[0,1] neg_hi:[0,1]
	v_mov_b32_e32 v70, v11
	v_mov_b32_e32 v71, v55
	v_pk_add_f32 v[8:9], v[74:75], v[60:61] op_sel_hi:[1,0] neg_lo:[0,1] neg_hi:[0,1]
	v_mov_b32_e32 v68, v10
	v_mov_b32_e32 v69, v54
	v_pk_mul_f32 v[70:71], v[70:71], v[70:71]
	v_add_f32_e32 v13, v80, v81
	v_pk_fma_f32 v[68:69], v[68:69], v[68:69], v[70:71]
	v_mov_b32_e32 v70, v8
	v_mov_b32_e32 v71, v52
	v_pk_fma_f32 v[68:69], v[70:71], v[70:71], v[68:69]
	v_mov_b32_e32 v70, v9
	v_mov_b32_e32 v71, v53
	v_pk_fma_f32 v[68:69], v[70:71], v[70:71], v[68:69]
	s_nop 0
	v_add_f32_e32 v13, v69, v13
	v_add_f32_e32 v13, v68, v13
	ds_bpermute_b32 v25, v61, v13
	s_waitcnt lgkmcnt(0)
	v_add_f32_e32 v13, v13, v25
	ds_bpermute_b32 v25, v62, v13
	s_waitcnt lgkmcnt(0)
	v_add_f32_e32 v13, v13, v25
	ds_bpermute_b32 v25, v63, v13
	s_waitcnt lgkmcnt(0)
	v_add_f32_e32 v13, v13, v25
	ds_bpermute_b32 v25, v64, v13
	s_waitcnt lgkmcnt(0)
	v_add_f32_e32 v13, v13, v25
	ds_bpermute_b32 v25, v65, v13
	s_waitcnt lgkmcnt(0)
	v_add_f32_e32 v13, v13, v25
	ds_bpermute_b32 v25, v66, v13
	s_waitcnt lgkmcnt(0)
	v_add_f32_e32 v13, v13, v25
	v_fmamk_f32 v13, v13, 0x3a800000, v252
	v_cmp_gt_f32_e32 vcc, s54, v13
	v_mul_f32_e32 v25, 0x4b800000, v13
	s_nop 0
	v_cndmask_b32_e32 v13, v13, v25, vcc
	v_rsq_f32_e32 v13, v13
	s_nop 0
	v_mul_f32_e32 v25, 0x45800000, v13
	v_cndmask_b32_e32 v60, v13, v25, vcc
	v_pk_mul_f32 v[68:69], v[76:77], v[60:61] op_sel_hi:[1,0]
	v_pk_mul_f32 v[10:11], v[10:11], v[60:61] op_sel_hi:[1,0]
	v_pk_fma_f32 v[0:1], v[0:1], v[68:69], v[4:5]
	v_pk_mul_f32 v[4:5], v[78:79], v[60:61] op_sel_hi:[1,0]
	v_cmp_lt_i32_e32 vcc, s55, v12
	v_pk_fma_f32 v[2:3], v[2:3], v[4:5], v[6:7]
	global_store_dwordx4 v[38:39], v[0:3], off
	s_nop 1
	s_nop 0
	s_or_b64 s[10:11], vcc, s[10:11]
	v_add_f32_e32 v13, 1.0, v104
	v_fma_f32 v0, v13, v0, v100
	v_add_f32_e32 v4, 1.0, v105
	v_fma_f32 v1, v4, v1, v101
	v_cvt_pk_bf16_f32 v0, v0, v1
	s_nop 1
	v_add_f32_e32 v1, 1.0, v106
	v_fma_f32 v1, v1, v2, v102
	v_add_f32_e32 v2, 1.0, v107
	v_fmac_f32_e32 v103, v2, v3
	v_cvt_pk_bf16_f32 v1, v1, v103
	s_nop 1
	global_store_dwordx2 v[36:37], v[0:1], off
	s_nop 0
	v_pk_mul_f32 v[48:49], v[58:59], v[60:61] op_sel_hi:[1,0]
	v_pk_fma_f32 v[0:1], v[48:49], v[108:109], v[112:113]
	v_pk_mul_f32 v[4:5], v[56:57], v[60:61] op_sel_hi:[1,0]
	s_nop 0
	v_pk_fma_f32 v[2:3], v[4:5], v[110:111], v[114:115]
	global_store_dwordx4 v[38:39], v[0:3], off offset:1024
	s_nop 1
	s_nop 0
	v_add_f32_e32 v13, 1.0, v120
	v_fma_f32 v0, v0, v13, v116
	v_add_f32_e32 v4, 1.0, v121
	v_fma_f32 v1, v1, v4, v117
	v_cvt_pk_bf16_f32 v0, v0, v1
	s_nop 1
	v_add_f32_e32 v1, 1.0, v122
	v_fma_f32 v1, v2, v1, v118
	v_add_f32_e32 v2, 1.0, v123
	v_fmac_f32_e32 v119, v3, v2
	v_cvt_pk_bf16_f32 v1, v1, v119
	s_nop 1
	global_store_dwordx2 v[36:37], v[0:1], off offset:512
	s_nop 0
	v_pk_mul_f32 v[44:45], v[54:55], v[60:61] op_sel_hi:[1,0]
	v_pk_fma_f32 v[0:1], v[44:45], v[124:125], v[128:129]
	v_pk_mul_f32 v[4:5], v[52:53], v[60:61] op_sel_hi:[1,0]
	s_nop 0
	v_pk_fma_f32 v[2:3], v[4:5], v[126:127], v[130:131]
	global_store_dwordx4 v[38:39], v[0:3], off offset:2048
	s_nop 1
	s_nop 0
	v_add_f32_e32 v13, 1.0, v136
	v_fma_f32 v0, v0, v13, v132
	v_add_f32_e32 v4, 1.0, v137
	v_fma_f32 v1, v1, v4, v133
	v_cvt_pk_bf16_f32 v0, v0, v1
	s_nop 1
	v_add_f32_e32 v1, 1.0, v138
	v_fma_f32 v1, v2, v1, v134
	v_add_f32_e32 v2, 1.0, v139
	v_fmac_f32_e32 v135, v3, v2
	v_cvt_pk_bf16_f32 v1, v1, v135
	s_nop 1
	global_store_dwordx2 v[36:37], v[0:1], off offset:1024
	s_nop 0
	v_pk_fma_f32 v[0:1], v[10:11], v[140:141], v[144:145]
	v_pk_mul_f32 v[4:5], v[8:9], v[60:61] op_sel_hi:[1,0]
	v_lshl_add_u64 v[8:9], v[32:33], 0, v[30:31]
	v_pk_fma_f32 v[2:3], v[4:5], v[142:143], v[146:147]
	global_store_dwordx4 v[38:39], v[0:3], off offset:3072
	s_nop 1
	v_lshl_add_u64 v[4:5], v[34:35], 0, v[30:31]
	s_nop 0
	v_add_f32_e32 v8, 1.0, v152
	v_fma_f32 v0, v0, v8, v148
	v_add_f32_e32 v4, 1.0, v153
	v_fma_f32 v1, v1, v4, v149
	v_cvt_pk_bf16_f32 v0, v0, v1
	s_nop 1
	v_add_f32_e32 v1, 1.0, v154
	v_fma_f32 v1, v2, v1, v150
	v_add_f32_e32 v2, 1.0, v155
	v_fmac_f32_e32 v151, v3, v2
	v_cvt_pk_bf16_f32 v1, v1, v151
	s_nop 1
	global_store_dwordx2 v[36:37], v[0:1], off offset:1536
	s_andn2_b64 exec, exec, s[10:11]
	s_cbranch_execnz .LBB0_896

.LBB0_1115:
	v_ashrrev_i32_e32 v9, 31, v8
	v_lshlrev_b64 v[0:1], 12, v[8:9]
	v_lshl_add_u64 v[50:51], v[26:27], 0, v[0:1]
	v_lshl_add_u64 v[30:31], v[28:29], 0, v[0:1]
	global_load_dwordx4 v[38:41], v[50:51], off
	global_load_dwordx4 v[0:3], v[10:11], off
	global_load_dwordx4 v[4:7], v[12:13], off
	global_load_dwordx4 v[42:45], v[50:51], off offset:1024
	v_add_u32_e32 v8, s47, v8
	global_load_dwordx4 v[100:103], v[50:51], off offset:2048
	global_load_dwordx4 v[104:107], v[50:51], off offset:3072
	global_load_dwordx4 v[108:111], v[14:15], off
	global_load_dwordx4 v[112:115], v[16:17], off
	global_load_dwordx4 v[116:119], v[18:19], off
	global_load_dwordx4 v[120:123], v[20:21], off
	global_load_dwordx4 v[124:127], v[22:23], off
	global_load_dwordx4 v[128:131], v[24:25], off
	s_waitcnt vmcnt(0)
	v_mov_b32_e32 v46, v38
	v_mov_b32_e32 v48, v39
	v_mov_b32_e32 v47, v42
	v_mov_b32_e32 v49, v43
	v_pk_add_f32 v[46:47], v[46:47], v[48:49]
	v_mov_b32_e32 v48, v40
	v_mov_b32_e32 v49, v44
	v_pk_add_f32 v[46:47], v[46:47], v[48:49]
	v_mov_b32_e32 v48, v41
	v_mov_b32_e32 v49, v45
	v_pk_add_f32 v[46:47], v[46:47], v[48:49]
	s_nop 0
	v_add_f32_e32 v9, 0, v46
	v_add_f32_e32 v9, v9, v47
	s_nop 0
	s_waitcnt vmcnt(1)
	v_mov_b32_e32 v54, v100
	v_mov_b32_e32 v55, v104
	v_mov_b32_e32 v56, v101
	v_mov_b32_e32 v57, v105
	v_pk_add_f32 v[54:55], v[54:55], v[56:57]
	v_mov_b32_e32 v56, v102
	v_mov_b32_e32 v57, v106
	v_pk_add_f32 v[54:55], v[54:55], v[56:57]
	v_mov_b32_e32 v56, v103
	v_mov_b32_e32 v57, v107
	v_pk_add_f32 v[54:55], v[54:55], v[56:57]
	s_nop 0
	v_add_f32_e32 v9, v9, v54
	v_add_f32_e32 v9, v9, v55
	ds_bpermute_b32 v54, v32, v9
	s_waitcnt lgkmcnt(0)
	v_add_f32_e32 v9, v9, v54
	ds_bpermute_b32 v54, v33, v9
	s_waitcnt lgkmcnt(0)
	v_add_f32_e32 v9, v9, v54
	ds_bpermute_b32 v54, v34, v9
	s_waitcnt lgkmcnt(0)
	v_add_f32_e32 v9, v9, v54
	ds_bpermute_b32 v54, v35, v9
	s_waitcnt lgkmcnt(0)
	v_add_f32_e32 v9, v9, v54
	ds_bpermute_b32 v54, v36, v9
	s_waitcnt lgkmcnt(0)
	v_add_f32_e32 v9, v9, v54
	ds_bpermute_b32 v54, v37, v9
	s_waitcnt lgkmcnt(0)
	v_add_f32_e32 v9, v9, v54
	v_mul_f32_e32 v54, 0x3a800000, v9
	v_pk_add_f32 v[38:39], v[38:39], v[54:55] op_sel_hi:[1,0] neg_lo:[0,1] neg_hi:[0,1]
	v_pk_add_f32 v[42:43], v[42:43], v[54:55] op_sel_hi:[1,0] neg_lo:[0,1] neg_hi:[0,1]
	v_mov_b32_e32 v58, v39
	v_mov_b32_e32 v59, v43
	v_pk_add_f32 v[40:41], v[40:41], v[54:55] op_sel_hi:[1,0] neg_lo:[0,1] neg_hi:[0,1]
	v_pk_add_f32 v[44:45], v[44:45], v[54:55] op_sel_hi:[1,0] neg_lo:[0,1] neg_hi:[0,1]
	v_mov_b32_e32 v56, v38
	v_mov_b32_e32 v57, v42
	v_pk_mul_f32 v[58:59], v[58:59], v[58:59]
	v_pk_add_f32 v[46:47], v[100:101], v[54:55] op_sel_hi:[1,0] neg_lo:[0,1] neg_hi:[0,1]
	v_pk_fma_f32 v[56:57], v[56:57], v[56:57], v[58:59]
	v_mov_b32_e32 v58, v40
	v_mov_b32_e32 v59, v44
	v_pk_fma_f32 v[56:57], v[58:59], v[58:59], v[56:57]
	v_mov_b32_e32 v58, v41
	v_mov_b32_e32 v59, v45
	v_pk_add_f32 v[50:51], v[104:105], v[54:55] op_sel_hi:[1,0] neg_lo:[0,1] neg_hi:[0,1]
	v_pk_fma_f32 v[56:57], v[58:59], v[58:59], v[56:57]
	v_mov_b32_e32 v58, v51
	v_mov_b32_e32 v59, v47
	v_pk_add_f32 v[48:49], v[102:103], v[54:55] op_sel_hi:[1,0] neg_lo:[0,1] neg_hi:[0,1]
	v_pk_add_f32 v[52:53], v[106:107], v[54:55] op_sel_hi:[1,0] neg_lo:[0,1] neg_hi:[0,1]
	v_mov_b32_e32 v54, v50
	v_mov_b32_e32 v55, v46
	v_pk_mul_f32 v[58:59], v[58:59], v[58:59]
	v_add_f32_e32 v9, v56, v57
	v_pk_fma_f32 v[54:55], v[54:55], v[54:55], v[58:59]
	v_mov_b32_e32 v58, v52
	v_mov_b32_e32 v59, v48
	v_pk_fma_f32 v[54:55], v[58:59], v[58:59], v[54:55]
	v_mov_b32_e32 v58, v53
	v_mov_b32_e32 v59, v49
	v_pk_fma_f32 v[54:55], v[58:59], v[58:59], v[54:55]
	s_nop 0
	v_add_f32_e32 v9, v55, v9
	v_add_f32_e32 v9, v54, v9
	ds_bpermute_b32 v54, v32, v9
	s_waitcnt lgkmcnt(0)
	v_add_f32_e32 v9, v9, v54
	ds_bpermute_b32 v54, v33, v9
	s_waitcnt lgkmcnt(0)
	v_add_f32_e32 v9, v9, v54
	ds_bpermute_b32 v54, v34, v9
	s_waitcnt lgkmcnt(0)
	v_add_f32_e32 v9, v9, v54
	ds_bpermute_b32 v54, v35, v9
	s_waitcnt lgkmcnt(0)
	v_add_f32_e32 v9, v9, v54
	ds_bpermute_b32 v54, v36, v9
	s_waitcnt lgkmcnt(0)
	v_add_f32_e32 v9, v9, v54
	ds_bpermute_b32 v54, v37, v9
	s_waitcnt lgkmcnt(0)
	v_add_f32_e32 v9, v9, v54
	v_fmamk_f32 v9, v9, 0x3a800000, v252
	v_cmp_gt_f32_e32 vcc, s54, v9
	v_mul_f32_e32 v54, 0x4b800000, v9
	s_nop 0
	v_cndmask_b32_e32 v9, v9, v54, vcc
	v_rsq_f32_e32 v9, v9
	s_nop 0
	v_mul_f32_e32 v54, 0x45800000, v9
	v_cndmask_b32_e32 v54, v9, v54, vcc
	v_pk_mul_f32 v[38:39], v[38:39], v[54:55] op_sel_hi:[1,0]
	v_cmp_lt_i32_e32 vcc, s55, v8
	v_pk_fma_f32 v[0:1], v[0:1], v[38:39], v[4:5]
	v_pk_mul_f32 v[4:5], v[40:41], v[54:55] op_sel_hi:[1,0]
	v_pk_mul_f32 v[38:39], v[42:43], v[54:55] op_sel_hi:[1,0]
	v_pk_fma_f32 v[2:3], v[2:3], v[4:5], v[6:7]
	global_store_dwordx4 v[30:31], v[0:3], off
	s_nop 1
	s_nop 0
	s_or_b64 s[4:5], vcc, s[4:5]
	v_pk_fma_f32 v[0:1], v[108:109], v[38:39], v[112:113]
	v_pk_mul_f32 v[4:5], v[44:45], v[54:55] op_sel_hi:[1,0]
	v_pk_mul_f32 v[38:39], v[46:47], v[54:55] op_sel_hi:[1,0]
	v_pk_fma_f32 v[2:3], v[110:111], v[4:5], v[114:115]
	global_store_dwordx4 v[30:31], v[0:3], off offset:1024
	s_nop 1
	s_nop 0
	v_pk_fma_f32 v[0:1], v[38:39], v[116:117], v[120:121]
	v_pk_mul_f32 v[4:5], v[48:49], v[54:55] op_sel_hi:[1,0]
	v_pk_mul_f32 v[38:39], v[50:51], v[54:55] op_sel_hi:[1,0]
	v_pk_fma_f32 v[2:3], v[4:5], v[118:119], v[122:123]
	global_store_dwordx4 v[30:31], v[0:3], off offset:2048
	s_nop 1
	s_nop 0
	v_pk_fma_f32 v[0:1], v[38:39], v[124:125], v[128:129]
	v_pk_mul_f32 v[4:5], v[52:53], v[54:55] op_sel_hi:[1,0]
	s_nop 0
	v_pk_fma_f32 v[2:3], v[4:5], v[126:127], v[130:131]
	global_store_dwordx4 v[30:31], v[0:3], off offset:3072
	s_nop 1
	s_andn2_b64 exec, exec, s[4:5]
	s_cbranch_execnz .LBB0_1115
